# moba_bucket QK^T: K-fragment ds_reads issued 5 ahead of their MFMAs through a 6-slot register ring (slot refilled one MFMA after its reader), counted lgkmcnt waits; same MFMAs in the same order
# speedup vs baseline: 1.0437x; 1.0051x over previous
.LBB0_1474:
	s_ashr_i32 s12, s14, 7
	s_ashr_i32 s13, s12, 31
	v_ashrrev_i32_e32 v40, 4, v53
	s_lshl_b64 s[22:23], s[12:13], 14
	v_ashrrev_i32_e32 v41, 31, v40
	v_lshl_add_u64 v[0:1], s[22:23], 0, v[40:41]
	s_bfe_u32 s11, s14, 0x10006
	v_mad_u64_u32 v[2:3], s[24:25], v0, s16, v[38:39]
	s_lshl_b32 s14, s14, 8
	s_and_b32 s24, s14, 0x3f00
	s_or_b32 s14, s22, s24
	s_mul_i32 s15, s23, 0xc00
	s_mul_hi_u32 s22, s14, 0xc00
	s_add_i32 s22, s22, s15
	s_mulk_i32 s14, 0xc00
	s_add_u32 s14, s76, s14
	s_addc_u32 s15, s77, s22
	s_lshl_b32 s22, s11, 7
	v_lshlrev_b32_e32 v0, 5, v53
	s_add_u32 s22, s14, s22
	v_and_b32_e32 v0, 0x180, v0
	s_addc_u32 s23, s15, 0
	s_lshl_b32 s14, s12, 1
	v_mad_i32_i24 v3, v1, s16, v3
	v_lshl_or_b32 v36, s11, 9, v0
	s_or_b32 s14, s14, s11
	v_mov_b32_e32 v58, v128
	v_lshl_add_u64 v[88:89], v[2:3], 0, v[36:37]
	s_add_i32 s14, s14, 4
	s_ashr_i32 s15, s14, 31
	v_lshlrev_b32_e32 v2, 4, v58
	v_add_u32_e32 v12, 0x100, v58
	v_and_b32_e32 v36, 0x70, v2
	v_ashrrev_i32_e32 v2, 31, v58
	v_ashrrev_i32_e32 v10, 31, v12
	v_add_u32_e32 v57, 0x400, v58
	s_lshl_b64 s[14:15], s[14:15], 21
	v_lshrrev_b32_e32 v2, 27, v2
	v_lshrrev_b32_e32 v10, 27, v10
	v_ashrrev_i32_e32 v34, 31, v57
	s_add_u32 s14, s80, s14
	v_add_u32_e32 v2, v58, v2
	v_add_u32_e32 v10, v12, v10
	v_lshrrev_b32_e32 v34, 27, v34
	s_addc_u32 s15, s81, s15
	s_lshl_b32 s24, s24, 1
	v_ashrrev_i32_e32 v96, 5, v2
	v_ashrrev_i32_e32 v100, 5, v10
	v_add_u32_e32 v34, v57, v34
	s_add_u32 s14, s14, s24
	v_lshlrev_b32_e32 v4, 3, v58
	v_ashrrev_i32_e32 v97, 31, v96
	v_lshlrev_b32_e32 v5, 8, v96
	v_ashrrev_i32_e32 v101, 31, v100
	v_ashrrev_i32_e32 v112, 5, v34
	s_addc_u32 s15, s15, 0
	v_ashrrev_i32_e32 v44, 3, v58
	v_mov_b64_e32 v[42:43], s[22:23]
	v_lshlrev_b64 v[2:3], 15, v[96:97]
	v_sub_u32_e32 v98, v4, v5
	v_lshlrev_b64 v[10:11], 15, v[100:101]
	v_add_u32_e32 v20, 0x200, v58
	v_ashrrev_i32_e32 v101, 3, v57
	v_lshlrev_b32_e32 v60, 8, v112
	v_lshlrev_b32_e32 v57, 3, v57
	v_mad_i64_i32 v[0:1], s[22:23], v44, s16, v[42:43]
	v_lshl_add_u64 v[2:3], s[14:15], 0, v[2:3]
	v_ashrrev_i32_e32 v99, 31, v98
	v_ashrrev_i32_e32 v18, 31, v20
	v_sub_u32_e32 v114, v57, v60
	v_add_u32_e32 v57, 0x500, v58
	v_lshl_add_u64 v[0:1], v[0:1], 0, v[36:37]
	v_lshl_add_u64 v[4:5], v[98:99], 1, v[2:3]
	v_ashrrev_i32_e32 v59, 3, v12
	v_lshlrev_b32_e32 v13, 8, v100
	v_lshlrev_b32_e32 v12, 3, v12
	v_lshrrev_b32_e32 v18, 27, v18
	v_ashrrev_i32_e32 v66, 31, v57
	global_load_dwordx4 v[0:3], v[0:1], off offset:2560
	s_nop 0
	global_load_dwordx4 v[4:7], v[4:5], off
	v_sub_u32_e32 v102, v12, v13
	v_add_u32_e32 v18, v20, v18
	v_add_u32_e32 v28, 0x300, v58
	v_lshrrev_b32_e32 v66, 27, v66
	v_mad_i64_i32 v[8:9], s[22:23], v59, s16, v[42:43]
	v_lshl_add_u64 v[10:11], s[14:15], 0, v[10:11]
	v_ashrrev_i32_e32 v103, 31, v102
	v_ashrrev_i32_e32 v104, 5, v18
	v_ashrrev_i32_e32 v26, 31, v28
	v_add_u32_e32 v66, v57, v66
	v_lshl_add_u64 v[8:9], v[8:9], 0, v[36:37]
	v_lshl_add_u64 v[12:13], v[102:103], 1, v[10:11]
	v_ashrrev_i32_e32 v97, 3, v20
	v_ashrrev_i32_e32 v105, 31, v104
	v_lshlrev_b32_e32 v21, 8, v104
	v_lshlrev_b32_e32 v20, 3, v20
	v_lshrrev_b32_e32 v26, 27, v26
	v_ashrrev_i32_e32 v116, 5, v66
	global_load_dwordx4 v[8:11], v[8:9], off offset:2560
	s_nop 0
	global_load_dwordx4 v[12:15], v[12:13], off
	v_lshlrev_b64 v[18:19], 15, v[104:105]
	v_sub_u32_e32 v106, v20, v21
	v_add_u32_e32 v26, v28, v26
	v_ashrrev_i32_e32 v103, 3, v57
	v_lshlrev_b32_e32 v68, 8, v116
	v_lshlrev_b32_e32 v57, 3, v57
	s_waitcnt lgkmcnt(0)
	v_mad_i64_i32 v[16:17], s[22:23], v97, s16, v[42:43]
	v_lshl_add_u64 v[18:19], s[14:15], 0, v[18:19]
	v_ashrrev_i32_e32 v107, 31, v106
	v_ashrrev_i32_e32 v108, 5, v26
	v_sub_u32_e32 v118, v57, v68
	v_add_u32_e32 v57, 0x600, v58
	v_lshl_add_u64 v[16:17], v[16:17], 0, v[36:37]
	v_lshl_add_u64 v[20:21], v[106:107], 1, v[18:19]
	v_ashrrev_i32_e32 v99, 3, v28
	v_ashrrev_i32_e32 v109, 31, v108
	v_lshlrev_b32_e32 v29, 8, v108
	v_lshlrev_b32_e32 v28, 3, v28
	v_ashrrev_i32_e32 v74, 31, v57
	global_load_dwordx4 v[16:19], v[16:17], off offset:2560
	s_nop 0
	global_load_dwordx4 v[20:23], v[20:21], off
	v_lshlrev_b64 v[26:27], 15, v[108:109]
	v_sub_u32_e32 v110, v28, v29
	v_lshrrev_b32_e32 v74, 27, v74
	v_mad_i64_i32 v[24:25], s[22:23], v99, s16, v[42:43]
	v_lshl_add_u64 v[26:27], s[14:15], 0, v[26:27]
	v_ashrrev_i32_e32 v111, 31, v110
	v_add_u32_e32 v74, v57, v74
	v_lshl_add_u64 v[24:25], v[24:25], 0, v[36:37]
	v_lshl_add_u64 v[28:29], v[110:111], 1, v[26:27]
	v_ashrrev_i32_e32 v113, 31, v112
	v_ashrrev_i32_e32 v120, 5, v74
	global_load_dwordx4 v[24:27], v[24:25], off offset:2560
	s_nop 0
	global_load_dwordx4 v[28:31], v[28:29], off
	v_lshlrev_b64 v[34:35], 15, v[112:113]
	v_ashrrev_i32_e32 v105, 3, v57
	v_lshlrev_b32_e32 v76, 8, v120
	v_lshlrev_b32_e32 v57, 3, v57
	v_mad_i64_i32 v[32:33], s[22:23], v101, s16, v[42:43]
	v_lshl_add_u64 v[34:35], s[14:15], 0, v[34:35]
	v_ashrrev_i32_e32 v115, 31, v114
	v_ashrrev_i32_e32 v117, 31, v116
	v_ashrrev_i32_e32 v121, 31, v120
	v_sub_u32_e32 v122, v57, v76
	v_add_u32_e32 v57, 0x700, v58
	v_lshl_add_u64 v[32:33], v[32:33], 0, v[36:37]
	v_lshl_add_u64 v[60:61], v[114:115], 1, v[34:35]
	v_lshlrev_b64 v[66:67], 15, v[116:117]
	v_lshlrev_b64 v[74:75], 15, v[120:121]
	v_ashrrev_i32_e32 v107, 3, v57
	global_load_dwordx4 v[32:35], v[32:33], off offset:2560
	s_nop 0
	global_load_dwordx4 v[60:63], v[60:61], off
	v_mad_i64_i32 v[64:65], s[22:23], v103, s16, v[42:43]
	v_lshl_add_u64 v[66:67], s[14:15], 0, v[66:67]
	v_ashrrev_i32_e32 v119, 31, v118
	v_mad_i64_i32 v[72:73], s[22:23], v105, s16, v[42:43]
	v_lshl_add_u64 v[74:75], s[14:15], 0, v[74:75]
	v_ashrrev_i32_e32 v123, 31, v122
	v_mad_i64_i32 v[42:43], s[22:23], v107, s16, v[42:43]
	v_lshl_add_u64 v[64:65], v[64:65], 0, v[36:37]
	v_lshl_add_u64 v[68:69], v[118:119], 1, v[66:67]
	v_lshl_add_u64 v[72:73], v[72:73], 0, v[36:37]
	v_lshl_add_u64 v[76:77], v[122:123], 1, v[74:75]
	v_lshl_add_u64 v[42:43], v[42:43], 0, v[36:37]
	global_load_dwordx4 v[64:67], v[64:65], off offset:2560
	s_nop 0
	global_load_dwordx4 v[68:71], v[68:69], off
	s_nop 0
	global_load_dwordx4 v[72:75], v[72:73], off offset:2560
	s_nop 0
	global_load_dwordx4 v[76:79], v[76:77], off
	v_cmp_lt_i32_e32 vcc, v49, v50
	global_load_dwordx4 v[80:83], v[42:43], off offset:2560
	v_ashrrev_i32_e32 v42, 31, v57
	v_lshrrev_b32_e32 v42, 27, v42
	v_add_u32_e32 v42, v57, v42
	v_ashrrev_i32_e32 v124, 5, v42
	v_ashrrev_i32_e32 v125, 31, v124
	v_lshlrev_b32_e32 v84, 8, v124
	v_lshlrev_b32_e32 v57, 3, v57
	v_lshlrev_b64 v[42:43], 15, v[124:125]
	v_sub_u32_e32 v126, v57, v84
	v_lshl_add_u64 v[42:43], s[14:15], 0, v[42:43]
	v_ashrrev_i32_e32 v127, 31, v126
	v_lshl_add_u64 v[42:43], v[126:127], 1, v[42:43]
	global_load_dwordx4 v[84:87], v[42:43], off
	v_bfe_u32 v57, v58, 4, 2
	v_lshlrev_b32_e32 v42, 4, v57
	v_mov_b32_e32 v43, v37
	v_lshl_add_u64 v[92:93], v[88:89], 0, v[42:43]
	global_load_dwordx4 v[88:91], v[92:93], off offset:1536
	s_nop 0
	global_load_dwordx4 v[92:95], v[92:93], off offset:1600
	v_mad_u64_u32 v[130:131], s[14:15], v44, s17, v[36:37]
	s_barrier
	s_waitcnt vmcnt(17)
	ds_write_b128 v130, v[0:3]
	v_mul_lo_u32 v0, v96, s18
	v_lshl_add_u32 v0, v98, 1, v0
	s_waitcnt vmcnt(16)
	ds_write_b128 v0, v[4:7] offset:40960
	v_mad_u64_u32 v[0:1], s[14:15], v59, s17, v[36:37]
	s_waitcnt vmcnt(15)
	ds_write_b128 v0, v[8:11]
	v_mul_lo_u32 v0, v100, s18
	v_lshl_add_u32 v0, v102, 1, v0
	s_waitcnt vmcnt(14)
	ds_write_b128 v0, v[12:15] offset:40960
	v_mad_u64_u32 v[0:1], s[14:15], v97, s17, v[36:37]
	s_waitcnt vmcnt(13)
	ds_write_b128 v0, v[16:19]
	v_mul_lo_u32 v0, v104, s18
	v_lshl_add_u32 v0, v106, 1, v0
	s_waitcnt vmcnt(12)
	ds_write_b128 v0, v[20:23] offset:40960
	v_mad_u64_u32 v[0:1], s[14:15], v99, s17, v[36:37]
	s_waitcnt vmcnt(11)
	ds_write_b128 v0, v[24:27]
	v_mul_lo_u32 v0, v108, s18
	v_lshl_add_u32 v0, v110, 1, v0
	s_waitcnt vmcnt(10)
	ds_write_b128 v0, v[28:31] offset:40960
	v_mad_u64_u32 v[0:1], s[14:15], v101, s17, v[36:37]
	v_and_b32_e32 v43, 15, v58
	s_waitcnt vmcnt(9)
	ds_write_b128 v0, v[32:35]
	v_mul_lo_u32 v0, v112, s18
	v_lshl_add_u32 v0, v114, 1, v0
	s_waitcnt vmcnt(8)
	ds_write_b128 v0, v[60:63] offset:40960
	v_mad_u64_u32 v[0:1], s[14:15], v103, s17, v[36:37]
	s_waitcnt vmcnt(7)
	ds_write_b128 v0, v[64:67]
	v_mul_lo_u32 v0, v116, s18
	v_lshl_add_u32 v0, v118, 1, v0
	s_waitcnt vmcnt(6)
	ds_write_b128 v0, v[68:71] offset:40960
	v_mad_u64_u32 v[0:1], s[14:15], v105, s17, v[36:37]
	s_waitcnt vmcnt(5)
	ds_write_b128 v0, v[72:75]
	v_mul_lo_u32 v0, v120, s18
	v_lshl_add_u32 v0, v122, 1, v0
	s_waitcnt vmcnt(4)
	ds_write_b128 v0, v[76:79] offset:40960
	v_mad_u64_u32 v[0:1], s[14:15], v107, s17, v[36:37]
	s_waitcnt vmcnt(3)
	ds_write_b128 v0, v[80:83]
	v_mul_lo_u32 v0, v124, s18
	v_lshl_add_u32 v0, v126, 1, v0
	v_mad_u32_u24 v36, v43, s17, v42
	v_mad_u32_u24 v42, v43, s18, v42
	s_waitcnt vmcnt(2)
	ds_write_b128 v0, v[84:87] offset:40960
	s_waitcnt lgkmcnt(0)
	s_barrier
	ds_read_b128 v[156:159], v36
	ds_read_b128 v[160:163], v36 offset:64
	ds_read_b128 v[164:167], v36 offset:2560
	ds_read_b128 v[168:171], v36 offset:2624
	ds_read_b128 v[172:175], v36 offset:5120
	s_waitcnt vmcnt(1)
	s_waitcnt lgkmcnt(4)
	v_mfma_f32_16x16x32_bf16 v[0:3], v[156:159], v[88:91], 0
	ds_read_b128 v[176:179], v36 offset:5184
	s_waitcnt vmcnt(0)
	s_waitcnt lgkmcnt(4)
	v_mfma_f32_16x16x32_bf16 v[60:63], v[160:163], v[92:95], v[0:3]
	ds_read_b128 v[156:159], v36 offset:7680
	s_waitcnt lgkmcnt(4)
	v_mfma_f32_16x16x32_bf16 v[4:7], v[164:167], v[88:91], 0
	ds_read_b128 v[160:163], v36 offset:7744
	s_waitcnt lgkmcnt(4)
	v_mfma_f32_16x16x32_bf16 v[64:67], v[168:171], v[92:95], v[4:7]
	ds_read_b128 v[164:167], v36 offset:10240
	s_waitcnt lgkmcnt(4)
	v_mfma_f32_16x16x32_bf16 v[4:7], v[172:175], v[88:91], 0
	ds_read_b128 v[168:171], v36 offset:10304
	s_waitcnt lgkmcnt(4)
	v_mfma_f32_16x16x32_bf16 v[68:71], v[176:179], v[92:95], v[4:7]
	ds_read_b128 v[172:175], v36 offset:12800
	s_waitcnt lgkmcnt(4)
	v_mfma_f32_16x16x32_bf16 v[4:7], v[156:159], v[88:91], 0
	ds_read_b128 v[176:179], v36 offset:12864
	s_waitcnt lgkmcnt(4)
	v_mfma_f32_16x16x32_bf16 v[72:75], v[160:163], v[92:95], v[4:7]
	ds_read_b128 v[156:159], v36 offset:15360
	s_waitcnt lgkmcnt(4)
	v_mfma_f32_16x16x32_bf16 v[4:7], v[164:167], v[88:91], 0
	ds_read_b128 v[160:163], v36 offset:15424
	s_waitcnt lgkmcnt(4)
	v_mfma_f32_16x16x32_bf16 v[76:79], v[168:171], v[92:95], v[4:7]
	ds_read_b128 v[164:167], v36 offset:17920
	s_waitcnt lgkmcnt(4)
	v_mfma_f32_16x16x32_bf16 v[4:7], v[172:175], v[88:91], 0
	ds_read_b128 v[168:171], v36 offset:17984
	s_waitcnt lgkmcnt(4)
	v_mfma_f32_16x16x32_bf16 v[80:83], v[176:179], v[92:95], v[4:7]
	ds_read_b128 v[172:175], v36 offset:20480
	s_waitcnt lgkmcnt(4)
	v_mfma_f32_16x16x32_bf16 v[4:7], v[156:159], v[88:91], 0
	ds_read_b128 v[176:179], v36 offset:20544
	s_waitcnt lgkmcnt(4)
	v_mfma_f32_16x16x32_bf16 v[84:87], v[160:163], v[92:95], v[4:7]
	ds_read_b128 v[156:159], v36 offset:23040
	s_waitcnt lgkmcnt(4)
	v_mfma_f32_16x16x32_bf16 v[4:7], v[164:167], v[88:91], 0
	ds_read_b128 v[160:163], v36 offset:23104
	s_waitcnt lgkmcnt(4)
	v_mfma_f32_16x16x32_bf16 v[32:35], v[168:171], v[92:95], v[4:7]
	ds_read_b128 v[164:167], v36 offset:25600
	s_waitcnt lgkmcnt(4)
	v_mfma_f32_16x16x32_bf16 v[4:7], v[172:175], v[88:91], 0
	ds_read_b128 v[168:171], v36 offset:25664
	s_waitcnt lgkmcnt(4)
	v_mfma_f32_16x16x32_bf16 v[28:31], v[176:179], v[92:95], v[4:7]
	ds_read_b128 v[172:175], v36 offset:28160
	s_waitcnt lgkmcnt(4)
	v_mfma_f32_16x16x32_bf16 v[4:7], v[156:159], v[88:91], 0
	ds_read_b128 v[176:179], v36 offset:28224
	s_waitcnt lgkmcnt(4)
	v_mfma_f32_16x16x32_bf16 v[24:27], v[160:163], v[92:95], v[4:7]
	ds_read_b128 v[156:159], v36 offset:30720
	s_waitcnt lgkmcnt(4)
	v_mfma_f32_16x16x32_bf16 v[4:7], v[164:167], v[88:91], 0
	ds_read_b128 v[160:163], v36 offset:30784
	s_waitcnt lgkmcnt(4)
	v_mfma_f32_16x16x32_bf16 v[20:23], v[168:171], v[92:95], v[4:7]
	ds_read_b128 v[164:167], v36 offset:33280
	s_waitcnt lgkmcnt(4)
	v_mfma_f32_16x16x32_bf16 v[4:7], v[172:175], v[88:91], 0
	ds_read_b128 v[168:171], v36 offset:33344
	s_waitcnt lgkmcnt(4)
	v_mfma_f32_16x16x32_bf16 v[16:19], v[176:179], v[92:95], v[4:7]
	ds_read_b128 v[172:175], v36 offset:35840
	s_waitcnt lgkmcnt(4)
	v_mfma_f32_16x16x32_bf16 v[4:7], v[156:159], v[88:91], 0
	ds_read_b128 v[176:179], v36 offset:35904
	s_waitcnt lgkmcnt(4)
	v_mfma_f32_16x16x32_bf16 v[12:15], v[160:163], v[92:95], v[4:7]
	ds_read_b128 v[156:159], v36 offset:38400
	s_waitcnt lgkmcnt(4)
	v_mfma_f32_16x16x32_bf16 v[4:7], v[164:167], v[88:91], 0
	ds_read_b128 v[160:163], v36 offset:38464
	s_waitcnt lgkmcnt(4)
	v_mfma_f32_16x16x32_bf16 v[8:11], v[168:171], v[92:95], v[4:7]
	s_waitcnt lgkmcnt(3)
	v_mfma_f32_16x16x32_bf16 v[4:7], v[172:175], v[88:91], 0
	s_waitcnt lgkmcnt(2)
	v_mfma_f32_16x16x32_bf16 v[4:7], v[176:179], v[92:95], v[4:7]
	v_max3_f32 v36, v60, s20, v61
	v_max_f32_e32 v44, v62, v63
	v_max_f32_e32 v59, v64, v65
	v_max_f32_e32 v152, v66, v67
	v_max3_f32 v36, v36, v68, v69
	v_max3_f32 v44, v44, v70, v71
	v_max3_f32 v59, v59, v72, v73
	v_max3_f32 v152, v152, v74, v75
	v_max3_f32 v36, v36, v76, v77
	v_max3_f32 v44, v44, v78, v79
	v_max3_f32 v59, v59, v80, v81
	v_max3_f32 v152, v152, v82, v83
	v_max3_f32 v36, v36, v84, v85
	v_max3_f32 v44, v44, v86, v87
	v_max3_f32 v59, v59, v32, v33
	v_max3_f32 v152, v152, v34, v35
	v_max3_f32 v36, v36, v28, v29
	v_max3_f32 v44, v44, v30, v31
	v_max3_f32 v59, v59, v24, v25
	v_max3_f32 v152, v152, v26, v27
	v_max3_f32 v36, v36, v20, v21
	s_waitcnt lgkmcnt(1)
	v_mfma_f32_16x16x32_bf16 v[88:91], v[156:159], v[88:91], 0
	v_max3_f32 v44, v44, v22, v23
	v_max3_f32 v59, v59, v16, v17
	v_max3_f32 v152, v152, v18, v19
	v_max3_f32 v36, v36, v12, v13
	s_waitcnt lgkmcnt(0)
	v_mfma_f32_16x16x32_bf16 v[0:3], v[160:163], v[92:95], v[88:91]
	v_max3_f32 v44, v44, v14, v15
	v_max3_f32 v59, v59, v8, v9
	v_max3_f32 v152, v152, v10, v11
	v_max3_f32 v36, v36, v4, v5
	v_max3_f32 v44, v44, v6, v7
	s_nop 2
	v_max3_f32 v59, v59, v0, v1
	v_max3_f32 v152, v152, v2, v3
	v_max3_f32 v36, v36, v44, v59
	v_max_f32_e32 v36, v36, v152
	v_mul_f32_e32 v36, 0x3e38aa3b, v36
	v_max_f32_e32 v36, s20, v36
	v_cndmask_b32_e32 v44, v48, v49, vcc
	v_lshlrev_b32_e32 v88, 2, v44
	ds_bpermute_b32 v44, v88, v36
	v_cmp_lt_i32_e32 vcc, v51, v50
	s_waitcnt lgkmcnt(0)
	s_barrier
	v_max_f32_e32 v44, v44, v44
	v_max_f32_e32 v36, v36, v44
	v_cndmask_b32_e32 v44, v48, v51, vcc
	v_lshlrev_b32_e32 v89, 2, v44
	ds_bpermute_b32 v59, v89, v36
	v_lshlrev_b32_e32 v44, 3, v57
	s_waitcnt lgkmcnt(0)
	v_max_f32_e32 v59, v59, v59
	v_max_f32_e32 v36, v36, v59
	v_fma_f32 v59, v60, s19, -v36
	v_fma_f32 v60, v61, s19, -v36
	v_fma_f32 v61, v62, s19, -v36
	v_fma_f32 v63, v63, s19, -v36
	v_fma_f32 v64, v64, s19, -v36
	v_fma_f32 v65, v65, s19, -v36
	v_fma_f32 v66, v66, s19, -v36
	v_fma_f32 v67, v67, s19, -v36
	v_fma_f32 v32, v32, s19, -v36
	v_fma_f32 v0, v0, s19, -v36
	v_exp_f32_e32 v59, v59
	v_exp_f32_e32 v60, v60
	v_exp_f32_e32 v61, v61
	v_exp_f32_e32 v63, v63
	v_exp_f32_e32 v64, v64
	v_exp_f32_e32 v65, v65
	v_exp_f32_e32 v66, v66
	v_exp_f32_e32 v67, v67
	v_fma_f32 v68, v68, s19, -v36
	v_fma_f32 v69, v69, s19, -v36
	v_fma_f32 v70, v70, s19, -v36
	v_fma_f32 v71, v71, s19, -v36
	v_fma_f32 v72, v72, s19, -v36
	v_fma_f32 v73, v73, s19, -v36
	v_fma_f32 v74, v74, s19, -v36
	v_fma_f32 v75, v75, s19, -v36
	v_exp_f32_e32 v91, v32
	v_fma_f32 v32, v33, s19, -v36
	v_fma_f32 v28, v28, s19, -v36
	v_fma_f32 v24, v24, s19, -v36
	v_fma_f32 v4, v4, s19, -v36
	v_exp_f32_e32 v123, v0
	v_fma_f32 v0, v1, s19, -v36
	v_ashrrev_i32_e32 v62, 2, v58
	v_exp_f32_e32 v68, v68
	v_exp_f32_e32 v69, v69
	v_exp_f32_e32 v70, v70
	v_exp_f32_e32 v71, v71
	v_exp_f32_e32 v72, v72
	v_exp_f32_e32 v73, v73
	v_exp_f32_e32 v74, v74
	v_exp_f32_e32 v75, v75
	v_fma_f32 v76, v76, s19, -v36
	v_fma_f32 v77, v77, s19, -v36
	v_fma_f32 v78, v78, s19, -v36
	v_fma_f32 v79, v79, s19, -v36
	v_fma_f32 v80, v80, s19, -v36
	v_fma_f32 v81, v81, s19, -v36
	v_fma_f32 v82, v82, s19, -v36
	v_fma_f32 v83, v83, s19, -v36
	v_exp_f32_e32 v92, v32
	v_fma_f32 v32, v34, s19, -v36
	v_exp_f32_e32 v95, v28
	v_fma_f32 v28, v29, s19, -v36
	v_exp_f32_e32 v99, v24
	v_fma_f32 v24, v25, s19, -v36
	v_fma_f32 v20, v20, s19, -v36
	v_fma_f32 v16, v16, s19, -v36
	v_exp_f32_e32 v119, v4
	v_fma_f32 v4, v5, s19, -v36
	v_exp_f32_e32 v124, v0
	v_fma_f32 v0, v2, s19, -v36
	v_exp_f32_e32 v76, v76
	v_exp_f32_e32 v77, v77
	v_exp_f32_e32 v78, v78
	v_exp_f32_e32 v79, v79
	v_exp_f32_e32 v80, v80
	v_exp_f32_e32 v81, v81
	v_exp_f32_e32 v82, v82
	v_exp_f32_e32 v83, v83
	v_fma_f32 v84, v84, s19, -v36
	v_fma_f32 v85, v85, s19, -v36
	v_fma_f32 v86, v86, s19, -v36
	v_fma_f32 v87, v87, s19, -v36
	v_exp_f32_e32 v93, v32
	v_fma_f32 v32, v35, s19, -v36
	v_exp_f32_e32 v96, v28
	v_fma_f32 v28, v30, s19, -v36
	v_exp_f32_e32 v100, v24
	v_fma_f32 v24, v26, s19, -v36
	v_exp_f32_e32 v103, v20
	v_fma_f32 v20, v21, s19, -v36
	v_exp_f32_e32 v107, v16
	v_fma_f32 v16, v17, s19, -v36
	v_fma_f32 v12, v12, s19, -v36
	v_fma_f32 v8, v8, s19, -v36
	v_exp_f32_e32 v120, v4
	v_fma_f32 v4, v6, s19, -v36
	v_exp_f32_e32 v125, v0
	v_fma_f32 v0, v3, s19, -v36
	v_bfi_b32 v127, -16, v62, v58
	v_exp_f32_e32 v84, v84
	v_exp_f32_e32 v85, v85
	v_exp_f32_e32 v86, v86
	v_exp_f32_e32 v87, v87
	v_exp_f32_e32 v94, v32
	v_exp_f32_e32 v97, v28
	v_fma_f32 v28, v31, s19, -v36
	v_exp_f32_e32 v101, v24
	v_fma_f32 v24, v27, s19, -v36
	v_exp_f32_e32 v104, v20
	v_fma_f32 v20, v22, s19, -v36
	v_exp_f32_e32 v108, v16
	v_fma_f32 v16, v18, s19, -v36
	v_exp_f32_e32 v111, v12
	v_fma_f32 v12, v13, s19, -v36
	v_exp_f32_e32 v115, v8
	v_fma_f32 v8, v9, s19, -v36
	v_exp_f32_e32 v121, v4
	v_fma_f32 v4, v7, s19, -v36
	v_exp_f32_e32 v126, v0
	v_mul_lo_u32 v0, v127, s18
	v_exp_f32_e32 v98, v28
	v_exp_f32_e32 v102, v24
	v_exp_f32_e32 v105, v20
	v_fma_f32 v20, v23, s19, -v36
	v_exp_f32_e32 v109, v16
	v_fma_f32 v16, v19, s19, -v36
	v_exp_f32_e32 v112, v12
	v_fma_f32 v12, v14, s19, -v36
	v_exp_f32_e32 v116, v8
	v_fma_f32 v8, v10, s19, -v36
	v_exp_f32_e32 v122, v4
	v_or_b32_e32 v4, v0, v44
	v_cvt_pk_bf16_f32 v0, v59, v60
	v_cvt_pk_bf16_f32 v1, v61, v63
	v_cvt_pk_bf16_f32 v2, v64, v65
	v_cvt_pk_bf16_f32 v3, v66, v67
	v_exp_f32_e32 v106, v20
	v_exp_f32_e32 v110, v16
	v_exp_f32_e32 v113, v12
	v_fma_f32 v12, v15, s19, -v36
	v_exp_f32_e32 v117, v8
	v_fma_f32 v8, v11, s19, -v36
	ds_write2_b64 v4, v[0:1], v[2:3] offset1:4
	v_cvt_pk_bf16_f32 v0, v68, v69
	v_cvt_pk_bf16_f32 v1, v70, v71
	v_cvt_pk_bf16_f32 v2, v72, v73
	v_cvt_pk_bf16_f32 v3, v74, v75
	v_exp_f32_e32 v114, v12
	v_exp_f32_e32 v118, v8
	ds_write2_b64 v4, v[0:1], v[2:3] offset0:8 offset1:12
	v_cvt_pk_bf16_f32 v0, v76, v77
	v_cvt_pk_bf16_f32 v1, v78, v79
	v_cvt_pk_bf16_f32 v2, v80, v81
	v_cvt_pk_bf16_f32 v3, v82, v83
	ds_write2_b64 v4, v[0:1], v[2:3] offset0:16 offset1:20
	v_cvt_pk_bf16_f32 v0, v84, v85
	v_cvt_pk_bf16_f32 v1, v86, v87
	v_cvt_pk_bf16_f32 v2, v91, v92
	v_cvt_pk_bf16_f32 v3, v93, v94
	ds_write2_b64 v4, v[0:1], v[2:3] offset0:24 offset1:28
	v_cvt_pk_bf16_f32 v0, v95, v96
	v_cvt_pk_bf16_f32 v1, v97, v98
	v_cvt_pk_bf16_f32 v2, v99, v100
	v_cvt_pk_bf16_f32 v3, v101, v102
	v_add_f32_e32 v90, 0, v59
	ds_write2_b64 v4, v[0:1], v[2:3] offset0:32 offset1:36
	v_cvt_pk_bf16_f32 v0, v103, v104
	v_cvt_pk_bf16_f32 v1, v105, v106
	v_cvt_pk_bf16_f32 v2, v107, v108
	v_cvt_pk_bf16_f32 v3, v109, v110
	v_add_f32_e32 v90, v60, v90
	ds_write2_b64 v4, v[0:1], v[2:3] offset0:40 offset1:44
	v_cvt_pk_bf16_f32 v0, v111, v112
	v_cvt_pk_bf16_f32 v1, v113, v114
	v_cvt_pk_bf16_f32 v2, v115, v116
	v_cvt_pk_bf16_f32 v3, v117, v118
	v_add_f32_e32 v90, v61, v90
	ds_write2_b64 v4, v[0:1], v[2:3] offset0:48 offset1:52
	v_cvt_pk_bf16_f32 v0, v119, v120
	v_cvt_pk_bf16_f32 v1, v121, v122
	v_cvt_pk_bf16_f32 v2, v123, v124
	v_cvt_pk_bf16_f32 v3, v125, v126
	v_add_f32_e32 v90, v63, v90
	ds_write2_b64 v4, v[0:1], v[2:3] offset0:56 offset1:60
	ds_read_b128 v[0:3], v42 offset:40960
	v_add_f32_e32 v90, v64, v90
	v_add_f32_e32 v90, v65, v90
	v_add_f32_e32 v90, v66, v90
	v_add_f32_e32 v12, v67, v90
	v_add_u32_e32 v43, v4, v44
	ds_read_b128 v[4:7], v43
	ds_read_b128 v[8:11], v42 offset:49664
	v_add_f32_e32 v32, v68, v12
	v_add_u32_e32 v66, 0x2200, v42
	ds_read_b128 v[12:15], v42 offset:58368
	ds_read_b128 v[16:19], v43 offset:64
	ds_read_b128 v[20:23], v42 offset:41024
	ds_read_b128 v[24:27], v66 offset:58368
	ds_read_b128 v[28:31], v42 offset:49728
	v_add_f32_e32 v32, v69, v32
	v_add_f32_e32 v58, v70, v32
	v_add_f32_e32 v58, v71, v58
	s_waitcnt lgkmcnt(6)
	v_mfma_f32_16x16x32_bf16 v[0:3], v[0:3], v[4:7], 0
	v_add_f32_e32 v62, v72, v58
	ds_read_b128 v[32:35], v42 offset:58432
	ds_read_b128 v[58:61], v66 offset:58432
	s_waitcnt lgkmcnt(7)
	v_mfma_f32_16x16x32_bf16 v[8:11], v[8:11], v[4:7], 0
	s_waitcnt lgkmcnt(6)
	v_mfma_f32_16x16x32_bf16 v[12:15], v[12:15], v[4:7], 0
	s_waitcnt lgkmcnt(3)
	v_mfma_f32_16x16x32_bf16 v[4:7], v[24:27], v[4:7], 0
	v_add_f32_e32 v24, v73, v62
	v_add_f32_e32 v24, v74, v24
	v_add_f32_e32 v24, v75, v24
	v_mfma_f32_16x16x32_bf16 v[0:3], v[20:23], v[16:19], v[0:3]
	v_add_f32_e32 v20, v76, v24
	v_add_f32_e32 v20, v77, v20
	v_add_f32_e32 v20, v78, v20
	v_add_f32_e32 v20, v79, v20
	v_add_f32_e32 v24, v80, v20
	ds_read_b128 v[20:23], v42 offset:41088
	s_waitcnt lgkmcnt(3)
	v_mfma_f32_16x16x32_bf16 v[8:11], v[28:31], v[16:19], v[8:11]
	v_add_f32_e32 v62, v81, v24
	ds_read_b128 v[24:27], v43 offset:128
	ds_read_b128 v[28:31], v42 offset:49792
	v_add_f32_e32 v67, v82, v62
	s_waitcnt lgkmcnt(4)
	v_mfma_f32_16x16x32_bf16 v[12:15], v[32:35], v[16:19], v[12:15]
	s_waitcnt lgkmcnt(3)
	v_mfma_f32_16x16x32_bf16 v[4:7], v[58:61], v[16:19], v[4:7]
	ds_read_b128 v[16:19], v42 offset:58496
	ds_read_b128 v[32:35], v43 offset:192
	ds_read_b128 v[58:61], v42 offset:41152
	s_waitcnt lgkmcnt(4)
	v_mfma_f32_16x16x32_bf16 v[0:3], v[20:23], v[24:27], v[0:3]
	ds_read_b128 v[20:23], v66 offset:58496
	ds_read_b128 v[62:65], v42 offset:49856
	s_waitcnt lgkmcnt(5)
	v_mfma_f32_16x16x32_bf16 v[8:11], v[28:31], v[24:27], v[8:11]
	v_add_f32_e32 v28, v83, v67
	v_add_f32_e32 v67, v84, v28
	ds_read_b128 v[28:31], v42 offset:58560
	s_waitcnt lgkmcnt(5)
	v_mfma_f32_16x16x32_bf16 v[12:15], v[16:19], v[24:27], v[12:15]
	v_add_f32_e32 v16, v85, v67
	v_add_f32_e32 v67, v86, v16
	ds_read_b128 v[16:19], v66 offset:58560
	s_waitcnt lgkmcnt(3)
	v_mfma_f32_16x16x32_bf16 v[4:7], v[20:23], v[24:27], v[4:7]
	v_add_f32_e32 v20, v87, v67
	v_add_f32_e32 v20, v91, v20
	v_add_f32_e32 v20, v92, v20
	v_add_f32_e32 v20, v93, v20
	v_add_f32_e32 v20, v94, v20
	v_add_f32_e32 v20, v95, v20
	v_add_f32_e32 v20, v96, v20
	v_add_f32_e32 v24, v97, v20
	ds_read_b128 v[20:23], v42 offset:41216
	s_waitcnt lgkmcnt(3)
	v_mfma_f32_16x16x32_bf16 v[8:11], v[62:65], v[32:35], v[8:11]
	v_add_f32_e32 v62, v98, v24
	v_add_f32_e32 v67, v99, v62
	s_waitcnt lgkmcnt(2)
	v_mfma_f32_16x16x32_bf16 v[12:15], v[28:31], v[32:35], v[12:15]
	ds_read_b128 v[24:27], v43 offset:256
	ds_read_b128 v[28:31], v42 offset:49920
	v_mfma_f32_16x16x32_bf16 v[0:3], v[58:61], v[32:35], v[0:3]
	s_waitcnt lgkmcnt(3)
	v_mfma_f32_16x16x32_bf16 v[4:7], v[16:19], v[32:35], v[4:7]
	ds_read_b128 v[16:19], v42 offset:58624
	ds_read_b128 v[32:35], v43 offset:320
	ds_read_b128 v[58:61], v42 offset:41280
	s_waitcnt lgkmcnt(4)
	v_mfma_f32_16x16x32_bf16 v[0:3], v[20:23], v[24:27], v[0:3]
	ds_read_b128 v[20:23], v66 offset:58624
	ds_read_b128 v[62:65], v42 offset:49984
	s_waitcnt lgkmcnt(5)
	v_mfma_f32_16x16x32_bf16 v[8:11], v[28:31], v[24:27], v[8:11]
	v_add_f32_e32 v28, v100, v67
	v_add_f32_e32 v67, v101, v28
	ds_read_b128 v[28:31], v42 offset:58688
	s_waitcnt lgkmcnt(5)
	v_mfma_f32_16x16x32_bf16 v[12:15], v[16:19], v[24:27], v[12:15]
	v_add_f32_e32 v16, v102, v67
	v_add_f32_e32 v67, v103, v16
	ds_read_b128 v[16:19], v66 offset:58688
	s_waitcnt lgkmcnt(3)
	v_mfma_f32_16x16x32_bf16 v[4:7], v[20:23], v[24:27], v[4:7]
	v_add_f32_e32 v20, v104, v67
	v_add_f32_e32 v20, v105, v20
	v_add_f32_e32 v20, v106, v20
	v_add_f32_e32 v20, v107, v20
	v_add_f32_e32 v20, v108, v20
	v_add_f32_e32 v20, v109, v20
	v_add_f32_e32 v20, v110, v20
	v_add_f32_e32 v24, v111, v20
	ds_read_b128 v[20:23], v42 offset:41344
	s_waitcnt lgkmcnt(3)
	v_mfma_f32_16x16x32_bf16 v[8:11], v[62:65], v[32:35], v[8:11]
	v_add_f32_e32 v62, v112, v24
	s_waitcnt lgkmcnt(2)
	v_mfma_f32_16x16x32_bf16 v[12:15], v[28:31], v[32:35], v[12:15]
	ds_read_b128 v[24:27], v43 offset:384
	ds_read_b128 v[28:31], v42 offset:50048
	v_mfma_f32_16x16x32_bf16 v[0:3], v[58:61], v[32:35], v[0:3]
	s_waitcnt lgkmcnt(3)
	v_mfma_f32_16x16x32_bf16 v[4:7], v[16:19], v[32:35], v[4:7]
	ds_read_b128 v[16:19], v42 offset:58752
	ds_read_b128 v[32:35], v43 offset:448
	ds_read_b128 v[58:61], v42 offset:41408
	v_add_f32_e32 v43, v113, v62
	s_waitcnt lgkmcnt(4)
	v_mfma_f32_16x16x32_bf16 v[0:3], v[20:23], v[24:27], v[0:3]
	ds_read_b128 v[20:23], v66 offset:58752
	ds_read_b128 v[62:65], v42 offset:50112
	ds_read_b128 v[66:69], v66 offset:58816
	s_waitcnt lgkmcnt(6)
	v_mfma_f32_16x16x32_bf16 v[8:11], v[28:31], v[24:27], v[8:11]
	v_add_f32_e32 v28, v114, v43
	v_add_f32_e32 v43, v115, v28
	ds_read_b128 v[28:31], v42 offset:58816
	s_waitcnt lgkmcnt(6)
	v_mfma_f32_16x16x32_bf16 v[16:19], v[16:19], v[24:27], v[12:15]
	s_nop 2
	v_add_f32_e32 v12, v116, v43
	v_add_f32_e32 v12, v117, v12
	s_waitcnt lgkmcnt(3)
	v_mfma_f32_16x16x32_bf16 v[20:23], v[20:23], v[24:27], v[4:7]
	s_nop 2
	v_add_f32_e32 v4, v118, v12
	v_add_f32_e32 v4, v119, v4
	v_add_f32_e32 v4, v120, v4
	v_mfma_f32_16x16x32_bf16 v[12:15], v[58:61], v[32:35], v[0:3]
	s_nop 2
	v_add_f32_e32 v0, v121, v4
	v_add_f32_e32 v0, v122, v0
	v_add_f32_e32 v0, v123, v0
	v_add_f32_e32 v0, v124, v0
	v_add_f32_e32 v0, v125, v0
	v_add_f32_e32 v0, v126, v0
	ds_bpermute_b32 v1, v88, v0
	s_waitcnt lgkmcnt(1)
	v_mfma_f32_16x16x32_bf16 v[4:7], v[28:31], v[32:35], v[16:19]
	s_waitcnt lgkmcnt(0)
	s_nop 1
	v_add_f32_e32 v16, v0, v1
	ds_bpermute_b32 v17, v89, v16
	v_mfma_f32_16x16x32_bf16 v[8:11], v[62:65], v[32:35], v[8:11]
	v_add_u32_e32 v18, v127, v55
	v_cmp_lt_i32_e32 vcc, v18, v45
	v_mfma_f32_16x16x32_bf16 v[0:3], v[66:69], v[32:35], v[20:23]
	s_and_saveexec_b64 s[14:15], vcc
	s_cbranch_execz .LBB0_1469
	s_waitcnt lgkmcnt(0)
	v_add_f32_e32 v17, v16, v17
	v_div_scale_f32 v16, s[22:23], v17, v17, 1.0
	v_rcp_f32_e32 v18, v16
	v_div_scale_f32 v19, vcc, 1.0, v17, 1.0
	s_lshl_b64 s[12:13], s[12:13], 17
	v_fma_f32 v20, -v16, v18, 1.0
	v_fmac_f32_e32 v18, v20, v18
	v_mul_f32_e32 v20, v19, v18
	v_fma_f32 v21, -v16, v20, v19
	v_fmac_f32_e32 v20, v21, v18
	v_fma_f32 v16, -v16, v20, v19
	v_div_fmas_f32 v16, v16, v18, v20
	s_lshl_b32 s11, s11, 2
	v_bfe_u32 v20, v53, 2, 2
	v_lshl_add_u64 v[18:19], v[40:41], 3, s[12:13]
	v_div_fixup_f32 v16, v16, v17, 1.0
	v_or3_b32 v18, v18, v20, s11
	v_lshlrev_b64 v[18:19], 2, v[18:19]
	v_pk_mul_f32 v[12:13], v[16:17], v[12:13] op_sel_hi:[0,1]
	v_and_or_b32 v18, v53, 3, v18
	v_cvt_pk_bf16_f32 v20, v12, v13
	v_pk_mul_f32 v[12:13], v[16:17], v[14:15] op_sel_hi:[0,1]
	v_readlane_b32 s12, v237, 40
	v_cvt_pk_bf16_f32 v21, v12, v13
	v_lshlrev_b64 v[12:13], 7, v[18:19]
	v_readlane_b32 s13, v237, 41
	v_mov_b32_e32 v45, v37
	v_cmp_eq_u32_e32 vcc, 0, v57
	v_lshl_add_u64 v[12:13], s[12:13], 0, v[12:13]
	v_lshl_add_u64 v[12:13], v[12:13], 0, v[44:45]
	global_store_dwordx2 v[12:13], v[20:21], off
	s_and_saveexec_b64 s[12:13], vcc
	s_cbranch_execz .LBB0_1468
	v_lshlrev_b64 v[14:15], 2, v[18:19]
	v_mul_f32_e32 v20, 0x3f317218, v36
	v_lshl_add_u64 v[18:19], s[2:3], 0, v[14:15]
	v_lshl_add_u64 v[14:15], s[8:9], 0, v[14:15]
	global_store_dword v[18:19], v20, off
	global_store_dword v[14:15], v17, off
	s_branch .LBB0_1468
